# next-unit scheduling arithmetic of the up-projection/in-projection GEMM phases sunk from the unit head into the MFMA gaps of the peeled first segment
# speedup vs baseline: 1.0088x; 1.0058x over previous
.LBB0_214:
	s_add_u32 s24, s24, 0x40080
	s_addc_u32 s25, s25, 0
	s_add_u32 s48, s26, 0x100
	s_addc_u32 s49, s27, 0
	s_mov_b32 s50, -2
	s_waitcnt lgkmcnt(0)
	v_xor_b32_e32 v246, 64, v153
	v_xor_b32_e32 v247, 64, v149
	v_add_u32_e32 v248, s42, v247
	v_add_u32_e32 v249, s43, v247
	ds_read_b128 v[144:147], v151
	ds_read_b128 v[154:157], v248
	ds_read_b128 v[158:161], v151 offset:2048
	ds_read_b128 v[162:165], v248 offset:2048
	ds_read_b128 v[166:169], v152
	ds_read_b128 v[170:173], v249
	ds_read_b128 v[174:177], v152 offset:2048
	ds_read_b128 v[178:181], v249 offset:2048
	s_add_u32 s26, s24, 0xfffc0080
	s_addc_u32 s27, s25, -1
	s_cmp_eq_u32 s50, 12
	s_cselect_b32 s29, s17, s27
	s_cselect_b32 s28, s46, s26
	s_cselect_b32 s27, s15, s49
	s_cselect_b32 s26, s47, s48
	v_lshl_add_u64 v[214:215], s[24:25], 0, v[136:137]
	s_add_i32 m0, s23, 0xc000
	ds_read_b128 v[182:185], v153
	ds_read_b128 v[186:189], v246
	ds_read_b128 v[190:193], v153 offset:2048
	ds_read_b128 v[194:197], v246 offset:2048
	ds_read_b128 v[198:201], v153 offset:4096
	ds_read_b128 v[202:205], v246 offset:4096
	ds_read_b128 v[206:209], v153 offset:6144
	ds_read_b128 v[210:213], v246 offset:6144
	global_load_lds_dwordx4 v[214:215], off
	v_lshl_add_u64 v[214:215], s[24:25], 0, v[138:139]
	s_add_i32 m0, s23, 0xe000
	s_nop 0
	global_load_lds_dwordx4 v[214:215], off
	s_waitcnt vmcnt(8)
	s_waitcnt lgkmcnt(0)
	s_barrier
	s_setprio 0
	s_waitcnt lgkmcnt(0)
	v_mfma_f32_16x16x32_bf16 v[124:127], v[144:147], v[182:185], 0
	s_add_i32 s37, s37, 1
	s_mul_i32 s6, s37, s38
	s_mul_hi_u32 s7, s37, s41
	v_mfma_f32_16x16x32_bf16 v[120:123], v[158:161], v[182:185], 0
	s_add_i32 s7, s7, s6
	s_mul_i32 s6, s37, s41
	s_add_u32 s18, s6, s96
	v_mfma_f32_16x16x32_bf16 v[108:111], v[144:147], v[190:193], 0
	s_addc_u32 s19, s7, s31
	v_cmp_lt_i64_e64 s[6:7], s[18:19], v[140:141]
	s_ashr_i32 s14, s18, 31
	v_mfma_f32_16x16x32_bf16 v[104:107], v[158:161], v[190:193], 0
	s_lshr_b32 s14, s14, 29
	s_add_i32 s14, s18, s14
	s_ashr_i32 s15, s14, 3
	v_mfma_f32_16x16x32_bf16 v[92:95], v[144:147], v[198:201], 0
	s_and_b32 s14, s14, -8
	s_sub_i32 s14, s18, s14
	s_cmp_lt_i32 s14, 0
	v_mfma_f32_16x16x32_bf16 v[88:91], v[158:161], v[198:201], 0
	s_cselect_b32 s16, s33, 0x160
	s_mul_i32 s14, s14, s16
	s_add_i32 s14, s14, s15
	v_mfma_f32_16x16x32_bf16 v[76:79], v[144:147], v[206:209], 0
	s_mul_hi_i32 s15, s14, 0x2e8ba2e9
	s_lshr_b32 s16, s15, 31
	s_ashr_i32 s15, s15, 5
	v_mfma_f32_16x16x32_bf16 v[72:75], v[158:161], v[206:209], 0
	s_add_i32 s15, s15, s16
	s_lshl_b32 s16, s15, 3
	s_sub_i32 s17, 0x80, s16
	v_mfma_f32_16x16x32_bf16 v[124:127], v[154:157], v[186:189], v[124:127]
	s_min_i32 s17, s17, 8
	s_abs_i32 s18, s17
	v_cvt_f32_u32_e32 v252, s18
	v_mfma_f32_16x16x32_bf16 v[120:123], v[162:165], v[186:189], v[120:123]
	s_sub_i32 s20, 0, s18
	s_mulk_i32 s15, 0xb0
	s_sub_i32 s15, s14, s15
	v_mfma_f32_16x16x32_bf16 v[108:111], v[154:157], v[194:197], v[108:111]
	v_rcp_iflag_f32_e32 v252, v252
	s_abs_i32 s14, s15
	s_xor_b32 s19, s15, s17
	v_mfma_f32_16x16x32_bf16 v[104:107], v[162:165], v[194:197], v[104:107]
	s_ashr_i32 s19, s19, 31
	v_mul_f32_e32 v252, 0x4f7ffffe, v252
	v_cvt_u32_f32_e32 v252, v252
	v_mfma_f32_16x16x32_bf16 v[92:95], v[154:157], v[202:205], v[92:95]
	s_nop 0
	v_readfirstlane_b32 s21, v252
	s_mul_i32 s20, s20, s21
	v_mfma_f32_16x16x32_bf16 v[88:91], v[162:165], v[202:205], v[88:91]
	s_mul_hi_u32 s20, s21, s20
	s_add_i32 s21, s21, s20
	s_mul_hi_u32 s20, s14, s21
	v_mfma_f32_16x16x32_bf16 v[76:79], v[154:157], v[210:213], v[76:79]
	s_mul_i32 s21, s20, s18
	s_sub_i32 s14, s14, s21
	s_add_i32 s98, s20, 1
	v_mfma_f32_16x16x32_bf16 v[72:75], v[162:165], v[210:213], v[72:75]
	s_sub_i32 s21, s14, s18
	s_cmp_ge_u32 s14, s18
	s_cselect_b32 s20, s98, s20
	s_setprio 0
	s_setprio 0
	v_mfma_f32_16x16x32_bf16 v[116:119], v[166:169], v[182:185], 0
	s_cselect_b32 s14, s21, s14
	s_add_i32 s21, s20, 1
	s_cmp_ge_u32 s14, s18
	v_mfma_f32_16x16x32_bf16 v[112:115], v[174:177], v[182:185], 0
	s_cselect_b32 s14, s21, s20
	s_xor_b32 s14, s14, s19
	s_sub_i32 s14, s14, s19
	v_mfma_f32_16x16x32_bf16 v[100:103], v[166:169], v[190:193], 0
	s_mul_i32 s17, s14, s17
	s_sub_i32 s15, s15, s17
	s_add_i32 s16, s16, s15
	v_mfma_f32_16x16x32_bf16 v[96:99], v[174:177], v[190:193], 0
	s_ashr_i32 s17, s16, 31
	s_lshl_b64 s[18:19], s[16:17], 19
	s_add_u32 s18, s90, s18
	v_mfma_f32_16x16x32_bf16 v[84:87], v[166:169], v[198:201], 0
	s_addc_u32 s19, s91, s19
	s_and_b64 s[20:21], s[6:7], exec
	s_cselect_b32 s17, s19, s25
	v_mfma_f32_16x16x32_bf16 v[80:83], v[174:177], v[198:201], 0
	s_cselect_b32 s46, s18, s24
	s_ashr_i32 s15, s14, 31
	s_lshl_b64 s[20:21], s[14:15], 19
	v_mfma_f32_16x16x32_bf16 v[68:71], v[166:169], v[206:209], 0
	s_add_u32 s20, s2, s20
	s_addc_u32 s21, s3, s21
	s_and_b64 s[98:99], s[6:7], exec
	v_mfma_f32_16x16x32_bf16 v[64:67], v[174:177], v[206:209], 0
	s_cselect_b32 s15, s21, s27
	s_cselect_b32 s47, s20, s26
	v_mfma_f32_16x16x32_bf16 v[116:119], v[170:173], v[186:189], v[116:119]
	v_mfma_f32_16x16x32_bf16 v[112:115], v[178:181], v[186:189], v[112:115]
	v_mfma_f32_16x16x32_bf16 v[100:103], v[170:173], v[194:197], v[100:103]
	v_mfma_f32_16x16x32_bf16 v[96:99], v[178:181], v[194:197], v[96:99]
	v_mfma_f32_16x16x32_bf16 v[84:87], v[170:173], v[202:205], v[84:87]
	v_mfma_f32_16x16x32_bf16 v[80:83], v[178:181], v[202:205], v[80:83]
	v_mfma_f32_16x16x32_bf16 v[68:71], v[170:173], v[210:213], v[68:71]
	v_mfma_f32_16x16x32_bf16 v[64:67], v[178:181], v[210:213], v[64:67]
	s_setprio 0
	s_barrier
	s_add_i32 s51, s42, s30
	v_lshl_add_u64 v[214:215], s[26:27], 0, v[132:133]
	s_mov_b32 m0, s51
	ds_read_b128 v[182:185], v153 offset:16384
	ds_read_b128 v[186:189], v246 offset:16384
	ds_read_b128 v[190:193], v153 offset:18432
	ds_read_b128 v[194:197], v246 offset:18432
	ds_read_b128 v[198:201], v153 offset:20480
	ds_read_b128 v[202:205], v246 offset:20480
	ds_read_b128 v[206:209], v153 offset:22528
	ds_read_b128 v[210:213], v246 offset:22528
	global_load_lds_dwordx4 v[214:215], off
	s_add_i32 m0, s51, 0x2000
	s_add_u32 s52, s26, 0x40000
	v_lshl_add_u64 v[216:217], s[26:27], 0, v[128:129]
	s_addc_u32 s53, s27, 0
	s_add_i32 s51, s43, s30
	global_load_lds_dwordx4 v[216:217], off
	v_lshl_add_u64 v[218:219], s[52:53], 0, v[132:133]
	s_mov_b32 m0, s51
	v_lshl_add_u64 v[220:221], s[28:29], 0, v[130:131]
	global_load_lds_dwordx4 v[218:219], off
	v_lshl_add_u64 v[218:219], s[52:53], 0, v[128:129]
	s_add_i32 m0, s51, 0x2000
	s_nop 0
	global_load_lds_dwordx4 v[218:219], off
	v_lshl_add_u64 v[218:219], s[28:29], 0, v[134:135]
	s_mov_b32 m0, s23
	s_nop 0
	global_load_lds_dwordx4 v[218:219], off
	s_mov_b32 m0, s34
	s_nop 0
	global_load_lds_dwordx4 v[220:221], off
	s_waitcnt vmcnt(8)
	s_waitcnt lgkmcnt(0)
	s_barrier
	s_setprio 0
	s_waitcnt lgkmcnt(0)
	v_mfma_f32_16x16x32_bf16 v[60:63], v[144:147], v[182:185], 0
	v_mfma_f32_16x16x32_bf16 v[56:59], v[158:161], v[182:185], 0
	v_mfma_f32_16x16x32_bf16 v[44:47], v[144:147], v[190:193], 0
	v_mfma_f32_16x16x32_bf16 v[40:43], v[158:161], v[190:193], 0
	v_mfma_f32_16x16x32_bf16 v[28:31], v[144:147], v[198:201], 0
	v_mfma_f32_16x16x32_bf16 v[24:27], v[158:161], v[198:201], 0
	v_mfma_f32_16x16x32_bf16 v[12:15], v[144:147], v[206:209], 0
	v_mfma_f32_16x16x32_bf16 v[8:11], v[158:161], v[206:209], 0
	v_mfma_f32_16x16x32_bf16 v[60:63], v[154:157], v[186:189], v[60:63]
	v_mfma_f32_16x16x32_bf16 v[56:59], v[162:165], v[186:189], v[56:59]
	v_mfma_f32_16x16x32_bf16 v[44:47], v[154:157], v[194:197], v[44:47]
	v_mfma_f32_16x16x32_bf16 v[40:43], v[162:165], v[194:197], v[40:43]
	v_mfma_f32_16x16x32_bf16 v[28:31], v[154:157], v[202:205], v[28:31]
	v_mfma_f32_16x16x32_bf16 v[24:27], v[162:165], v[202:205], v[24:27]
	v_mfma_f32_16x16x32_bf16 v[12:15], v[154:157], v[210:213], v[12:15]
	v_mfma_f32_16x16x32_bf16 v[8:11], v[162:165], v[210:213], v[8:11]
	s_setprio 0
	s_setprio 0
	v_mfma_f32_16x16x32_bf16 v[52:55], v[166:169], v[182:185], 0
	v_mfma_f32_16x16x32_bf16 v[48:51], v[174:177], v[182:185], 0
	v_mfma_f32_16x16x32_bf16 v[36:39], v[166:169], v[190:193], 0
	v_mfma_f32_16x16x32_bf16 v[32:35], v[174:177], v[190:193], 0
	v_mfma_f32_16x16x32_bf16 v[20:23], v[166:169], v[198:201], 0
	v_mfma_f32_16x16x32_bf16 v[16:19], v[174:177], v[198:201], 0
	v_mfma_f32_16x16x32_bf16 v[4:7], v[166:169], v[206:209], 0
	v_mfma_f32_16x16x32_bf16 v[0:3], v[174:177], v[206:209], 0
	v_mfma_f32_16x16x32_bf16 v[52:55], v[170:173], v[186:189], v[52:55]
	v_mfma_f32_16x16x32_bf16 v[48:51], v[178:181], v[186:189], v[48:51]
	v_mfma_f32_16x16x32_bf16 v[36:39], v[170:173], v[194:197], v[36:39]
	v_mfma_f32_16x16x32_bf16 v[32:35], v[178:181], v[194:197], v[32:35]
	v_mfma_f32_16x16x32_bf16 v[20:23], v[170:173], v[202:205], v[20:23]
	v_mfma_f32_16x16x32_bf16 v[16:19], v[178:181], v[202:205], v[16:19]
	v_mfma_f32_16x16x32_bf16 v[4:7], v[170:173], v[210:213], v[4:7]
	v_mfma_f32_16x16x32_bf16 v[0:3], v[178:181], v[210:213], v[0:3]
	s_setprio 0
	s_barrier
	s_add_i32 s51, 0, 0x18000
	s_add_i32 s52, 0, 0x1c000
	v_add_u32_e32 v162, s51, v149
	v_add_u32_e32 v250, s51, v247
	v_add_u32_e32 v178, s52, v149
	v_add_u32_e32 v251, s52, v247
	ds_read_b128 v[144:147], v162
	ds_read_b128 v[154:157], v250
	ds_read_b128 v[158:161], v162 offset:2048
	ds_read_b128 v[162:165], v250 offset:2048
	ds_read_b128 v[166:169], v178
	ds_read_b128 v[170:173], v251
	ds_read_b128 v[174:177], v178 offset:2048
	ds_read_b128 v[178:181], v251 offset:2048
	s_add_u32 s28, s28, 0x40000
	s_addc_u32 s29, s29, 0
	s_mov_b32 m0, s35
	v_lshl_add_u64 v[222:223], s[28:29], 0, v[134:135]
	ds_read_b128 v[182:185], v153 offset:32768
	ds_read_b128 v[186:189], v246 offset:32768
	ds_read_b128 v[190:193], v153 offset:34816
	ds_read_b128 v[194:197], v246 offset:34816
	ds_read_b128 v[198:201], v153 offset:36864
	ds_read_b128 v[202:205], v246 offset:36864
	ds_read_b128 v[206:209], v153 offset:38912
	ds_read_b128 v[210:213], v246 offset:38912
	global_load_lds_dwordx4 v[222:223], off
	v_lshl_add_u64 v[222:223], s[28:29], 0, v[130:131]
	s_mov_b32 m0, s36
	s_nop 0
	global_load_lds_dwordx4 v[222:223], off
	s_waitcnt vmcnt(8)
	s_waitcnt lgkmcnt(0)
	s_barrier
	s_setprio 0
	s_waitcnt lgkmcnt(0)
	v_mfma_f32_16x16x32_bf16 v[124:127], v[144:147], v[182:185], v[124:127]
	v_mfma_f32_16x16x32_bf16 v[120:123], v[158:161], v[182:185], v[120:123]
	v_mfma_f32_16x16x32_bf16 v[108:111], v[144:147], v[190:193], v[108:111]
	v_mfma_f32_16x16x32_bf16 v[104:107], v[158:161], v[190:193], v[104:107]
	v_mfma_f32_16x16x32_bf16 v[92:95], v[144:147], v[198:201], v[92:95]
	v_mfma_f32_16x16x32_bf16 v[88:91], v[158:161], v[198:201], v[88:91]
	v_mfma_f32_16x16x32_bf16 v[76:79], v[144:147], v[206:209], v[76:79]
	v_mfma_f32_16x16x32_bf16 v[72:75], v[158:161], v[206:209], v[72:75]
	v_mfma_f32_16x16x32_bf16 v[124:127], v[154:157], v[186:189], v[124:127]
	v_mfma_f32_16x16x32_bf16 v[120:123], v[162:165], v[186:189], v[120:123]
	v_mfma_f32_16x16x32_bf16 v[108:111], v[154:157], v[194:197], v[108:111]
	v_mfma_f32_16x16x32_bf16 v[104:107], v[162:165], v[194:197], v[104:107]
	v_mfma_f32_16x16x32_bf16 v[92:95], v[154:157], v[202:205], v[92:95]
	v_mfma_f32_16x16x32_bf16 v[88:91], v[162:165], v[202:205], v[88:91]
	v_mfma_f32_16x16x32_bf16 v[76:79], v[154:157], v[210:213], v[76:79]
	v_mfma_f32_16x16x32_bf16 v[72:75], v[162:165], v[210:213], v[72:75]
	s_setprio 0
	s_setprio 0
	v_mfma_f32_16x16x32_bf16 v[116:119], v[166:169], v[182:185], v[116:119]
	v_mfma_f32_16x16x32_bf16 v[112:115], v[174:177], v[182:185], v[112:115]
	v_mfma_f32_16x16x32_bf16 v[100:103], v[166:169], v[190:193], v[100:103]
	v_mfma_f32_16x16x32_bf16 v[96:99], v[174:177], v[190:193], v[96:99]
	v_mfma_f32_16x16x32_bf16 v[84:87], v[166:169], v[198:201], v[84:87]
	v_mfma_f32_16x16x32_bf16 v[80:83], v[174:177], v[198:201], v[80:83]
	v_mfma_f32_16x16x32_bf16 v[68:71], v[166:169], v[206:209], v[68:71]
	v_mfma_f32_16x16x32_bf16 v[64:67], v[174:177], v[206:209], v[64:67]
	v_mfma_f32_16x16x32_bf16 v[116:119], v[170:173], v[186:189], v[116:119]
	v_mfma_f32_16x16x32_bf16 v[112:115], v[178:181], v[186:189], v[112:115]
	v_mfma_f32_16x16x32_bf16 v[100:103], v[170:173], v[194:197], v[100:103]
	v_mfma_f32_16x16x32_bf16 v[96:99], v[178:181], v[194:197], v[96:99]
	v_mfma_f32_16x16x32_bf16 v[84:87], v[170:173], v[202:205], v[84:87]
	v_mfma_f32_16x16x32_bf16 v[80:83], v[178:181], v[202:205], v[80:83]
	v_mfma_f32_16x16x32_bf16 v[68:71], v[170:173], v[210:213], v[68:71]
	v_mfma_f32_16x16x32_bf16 v[64:67], v[178:181], v[210:213], v[64:67]
	s_setprio 0
	s_barrier
	s_add_i32 s28, s51, s30
	v_lshl_add_u64 v[214:215], v[214:215], 0, s[10:11]
	s_mov_b32 m0, s28
	ds_read_b128 v[182:185], v153 offset:49152
	ds_read_b128 v[186:189], v246 offset:49152
	ds_read_b128 v[190:193], v153 offset:51200
	ds_read_b128 v[194:197], v246 offset:51200
	ds_read_b128 v[198:201], v153 offset:53248
	ds_read_b128 v[202:205], v246 offset:53248
	ds_read_b128 v[206:209], v153 offset:55296
	ds_read_b128 v[210:213], v246 offset:55296
	global_load_lds_dwordx4 v[214:215], off
	s_add_i32 m0, s28, 0x2000
	s_add_u32 s26, s26, 0x40080
	v_lshl_add_u64 v[214:215], v[216:217], 0, s[10:11]
	s_addc_u32 s27, s27, 0
	s_add_i32 s28, s52, s30
	global_load_lds_dwordx4 v[214:215], off
	v_lshl_add_u64 v[214:215], s[26:27], 0, v[132:133]
	s_mov_b32 m0, s28
	s_nop 0
	global_load_lds_dwordx4 v[214:215], off
	v_lshl_add_u64 v[214:215], s[26:27], 0, v[128:129]
	s_add_i32 m0, s28, 0x2000
	s_nop 0
	global_load_lds_dwordx4 v[214:215], off
	v_lshl_add_u64 v[214:215], v[218:219], 0, s[10:11]
	s_mov_b32 m0, s39
	s_nop 0
	global_load_lds_dwordx4 v[214:215], off
	v_lshl_add_u64 v[214:215], v[220:221], 0, s[10:11]
	s_mov_b32 m0, s40
	s_nop 0
	global_load_lds_dwordx4 v[214:215], off
	s_waitcnt vmcnt(8)
	s_waitcnt lgkmcnt(0)
	s_barrier
	s_setprio 0
	s_waitcnt lgkmcnt(0)
	v_mfma_f32_16x16x32_bf16 v[60:63], v[144:147], v[182:185], v[60:63]
	v_mfma_f32_16x16x32_bf16 v[56:59], v[158:161], v[182:185], v[56:59]
	v_mfma_f32_16x16x32_bf16 v[44:47], v[144:147], v[190:193], v[44:47]
	v_mfma_f32_16x16x32_bf16 v[40:43], v[158:161], v[190:193], v[40:43]
	v_mfma_f32_16x16x32_bf16 v[28:31], v[144:147], v[198:201], v[28:31]
	v_mfma_f32_16x16x32_bf16 v[24:27], v[158:161], v[198:201], v[24:27]
	v_mfma_f32_16x16x32_bf16 v[12:15], v[144:147], v[206:209], v[12:15]
	v_mfma_f32_16x16x32_bf16 v[8:11], v[158:161], v[206:209], v[8:11]
	v_mfma_f32_16x16x32_bf16 v[60:63], v[154:157], v[186:189], v[60:63]
	v_mfma_f32_16x16x32_bf16 v[56:59], v[162:165], v[186:189], v[56:59]
	v_mfma_f32_16x16x32_bf16 v[44:47], v[154:157], v[194:197], v[44:47]
	v_mfma_f32_16x16x32_bf16 v[40:43], v[162:165], v[194:197], v[40:43]
	v_mfma_f32_16x16x32_bf16 v[28:31], v[154:157], v[202:205], v[28:31]
	v_mfma_f32_16x16x32_bf16 v[24:27], v[162:165], v[202:205], v[24:27]
	v_mfma_f32_16x16x32_bf16 v[12:15], v[154:157], v[210:213], v[12:15]
	v_mfma_f32_16x16x32_bf16 v[8:11], v[162:165], v[210:213], v[8:11]
	s_setprio 0
	s_setprio 0
	v_mfma_f32_16x16x32_bf16 v[52:55], v[166:169], v[182:185], v[52:55]
	v_mfma_f32_16x16x32_bf16 v[48:51], v[174:177], v[182:185], v[48:51]
	v_mfma_f32_16x16x32_bf16 v[36:39], v[166:169], v[190:193], v[36:39]
	v_mfma_f32_16x16x32_bf16 v[32:35], v[174:177], v[190:193], v[32:35]
	v_mfma_f32_16x16x32_bf16 v[20:23], v[166:169], v[198:201], v[20:23]
	v_mfma_f32_16x16x32_bf16 v[16:19], v[174:177], v[198:201], v[16:19]
	v_mfma_f32_16x16x32_bf16 v[4:7], v[166:169], v[206:209], v[4:7]
	v_mfma_f32_16x16x32_bf16 v[0:3], v[174:177], v[206:209], v[0:3]
	v_mfma_f32_16x16x32_bf16 v[52:55], v[170:173], v[186:189], v[52:55]
	v_mfma_f32_16x16x32_bf16 v[48:51], v[178:181], v[186:189], v[48:51]
	v_mfma_f32_16x16x32_bf16 v[36:39], v[170:173], v[194:197], v[36:39]
	v_mfma_f32_16x16x32_bf16 v[32:35], v[178:181], v[194:197], v[32:35]
	v_mfma_f32_16x16x32_bf16 v[20:23], v[170:173], v[202:205], v[20:23]
	v_mfma_f32_16x16x32_bf16 v[16:19], v[178:181], v[202:205], v[16:19]
	v_mfma_f32_16x16x32_bf16 v[4:7], v[170:173], v[210:213], v[4:7]
	v_mfma_f32_16x16x32_bf16 v[0:3], v[178:181], v[210:213], v[0:3]
	s_setprio 0
	s_barrier
	s_add_i32 s50, s50, 2
	s_add_u32 s24, s24, 0x100
	s_addc_u32 s25, s25, 0
	s_add_u32 s48, s48, 0x100
	s_addc_u32 s49, s49, 0
	s_cmp_gt_u32 s50, 13

.LBB0_430:
	s_add_u32 s28, s28, 0x40080
	s_addc_u32 s29, s29, 0
	s_add_u32 s56, s30, 0x100
	s_addc_u32 s57, s31, 0
	s_mov_b32 s58, -2
	v_xor_b32_e32 v246, 64, v241
	v_xor_b32_e32 v247, 64, v237
	v_add_u32_e32 v248, s50, v247
	v_add_u32_e32 v249, s51, v247
	ds_read_b128 v[130:133], v239
	ds_read_b128 v[134:137], v248
	ds_read_b128 v[138:141], v239 offset:2048
	ds_read_b128 v[142:145], v248 offset:2048
	ds_read_b128 v[146:149], v240
	ds_read_b128 v[150:153], v249
	ds_read_b128 v[154:157], v240 offset:2048
	ds_read_b128 v[158:161], v249 offset:2048
	s_add_u32 s30, s28, 0xfffc0080
	s_addc_u32 s31, s29, -1
	s_cmp_eq_u32 s58, 12
	s_cselect_b32 s35, s9, s31
	s_cselect_b32 s34, s23, s30
	s_cselect_b32 s31, s21, s57
	s_cselect_b32 s30, s55, s56
	v_lshl_add_u64 v[80:81], s[28:29], 0, v[222:223]
	s_add_i32 m0, s36, 0xc000
	ds_read_b128 v[162:165], v241
	ds_read_b128 v[166:169], v246
	ds_read_b128 v[170:173], v241 offset:2048
	ds_read_b128 v[174:177], v246 offset:2048
	ds_read_b128 v[178:181], v241 offset:4096
	ds_read_b128 v[182:185], v246 offset:4096
	ds_read_b128 v[186:189], v241 offset:6144
	ds_read_b128 v[190:193], v246 offset:6144
	global_load_lds_dwordx4 v[80:81], off
	v_lshl_add_u64 v[80:81], s[28:29], 0, v[224:225]
	s_add_i32 m0, s36, 0xe000
	s_nop 0
	global_load_lds_dwordx4 v[80:81], off
	s_waitcnt vmcnt(8)
	s_waitcnt lgkmcnt(0)
	s_barrier
	s_setprio 0
	s_waitcnt lgkmcnt(0)
	v_mfma_f32_16x16x32_bf16 v[126:129], v[130:133], v[162:165], 0
	s_add_i32 s54, s54, 1
	s_mul_i32 s6, s54, s44
	s_mul_hi_u32 s7, s54, s49
	v_mfma_f32_16x16x32_bf16 v[122:125], v[138:141], v[162:165], 0
	s_add_i32 s7, s7, s6
	s_mul_i32 s6, s54, s49
	s_add_u32 s24, s6, s96
	v_mfma_f32_16x16x32_bf16 v[110:113], v[130:133], v[170:173], 0
	s_addc_u32 s25, s7, s45
	v_cmp_lt_i64_e64 s[6:7], s[24:25], v[226:227]
	s_ashr_i32 s9, s24, 31
	v_mfma_f32_16x16x32_bf16 v[106:109], v[138:141], v[170:173], 0
	s_lshr_b32 s9, s9, 29
	s_add_i32 s9, s24, s9
	s_ashr_i32 s20, s9, 3
	v_mfma_f32_16x16x32_bf16 v[94:97], v[130:133], v[178:181], 0
	s_and_b32 s9, s9, -8
	s_sub_i32 s9, s24, s9
	s_cmp_lt_i32 s9, 0
	v_mfma_f32_16x16x32_bf16 v[90:93], v[138:141], v[178:181], 0
	s_movk_i32 s21, 0xe1
	s_cselect_b32 s21, s21, 0xe0
	s_mul_i32 s9, s9, s21
	v_mfma_f32_16x16x32_bf16 v[76:79], v[130:133], v[186:189], 0
	s_add_i32 s9, s9, s20
	s_mul_hi_i32 s20, s9, 0x92492493
	s_add_i32 s20, s20, s9
	v_mfma_f32_16x16x32_bf16 v[72:75], v[138:141], v[186:189], 0
	s_lshr_b32 s21, s20, 31
	s_ashr_i32 s20, s20, 6
	s_add_i32 s20, s20, s21
	v_mfma_f32_16x16x32_bf16 v[126:129], v[134:137], v[166:169], v[126:129]
	s_lshl_b32 s21, s20, 3
	s_sub_i32 s22, 0x80, s21
	s_min_i32 s22, s22, 8
	v_mfma_f32_16x16x32_bf16 v[122:125], v[142:145], v[166:169], v[122:125]
	s_abs_i32 s23, s22
	v_cvt_f32_u32_e32 v252, s23
	s_sub_i32 s25, 0, s23
	v_mfma_f32_16x16x32_bf16 v[110:113], v[134:137], v[174:177], v[110:113]
	s_mulk_i32 s20, 0x70
	s_sub_i32 s9, s9, s20
	v_rcp_iflag_f32_e32 v252, v252
	v_mfma_f32_16x16x32_bf16 v[106:109], v[142:145], v[174:177], v[106:109]
	s_abs_i32 s20, s9
	s_xor_b32 s24, s9, s22
	s_ashr_i32 s24, s24, 31
	v_mfma_f32_16x16x32_bf16 v[94:97], v[134:137], v[182:185], v[94:97]
	v_mul_f32_e32 v252, 0x4f7ffffe, v252
	v_cvt_u32_f32_e32 v252, v252
	s_nop 0
	v_mfma_f32_16x16x32_bf16 v[90:93], v[142:145], v[182:185], v[90:93]
	v_readfirstlane_b32 s26, v252
	s_mul_i32 s25, s25, s26
	s_mul_hi_u32 s25, s26, s25
	v_mfma_f32_16x16x32_bf16 v[76:79], v[134:137], v[190:193], v[76:79]
	s_add_i32 s26, s26, s25
	s_mul_hi_u32 s25, s20, s26
	s_mul_i32 s26, s25, s23
	v_mfma_f32_16x16x32_bf16 v[72:75], v[142:145], v[190:193], v[72:75]
	s_sub_i32 s20, s20, s26
	s_add_i32 s27, s25, 1
	s_sub_i32 s26, s20, s23
	s_setprio 0
	s_setprio 0
	v_mfma_f32_16x16x32_bf16 v[118:121], v[146:149], v[162:165], 0
	s_cmp_ge_u32 s20, s23
	s_cselect_b32 s25, s27, s25
	s_cselect_b32 s20, s26, s20
	v_mfma_f32_16x16x32_bf16 v[114:117], v[154:157], v[162:165], 0
	s_add_i32 s26, s25, 1
	s_cmp_ge_u32 s20, s23
	s_cselect_b32 s20, s26, s25
	v_mfma_f32_16x16x32_bf16 v[102:105], v[146:149], v[170:173], 0
	s_xor_b32 s20, s20, s24
	s_sub_i32 s20, s20, s24
	s_mul_i32 s22, s20, s22
	v_mfma_f32_16x16x32_bf16 v[98:101], v[154:157], v[170:173], 0
	s_sub_i32 s9, s9, s22
	s_add_i32 s22, s21, s9
	s_ashr_i32 s23, s22, 31
	v_mfma_f32_16x16x32_bf16 v[86:89], v[146:149], v[178:181], 0
	s_lshl_b64 s[24:25], s[22:23], 19
	s_add_u32 s24, s90, s24
	s_addc_u32 s25, s91, s25
	v_mfma_f32_16x16x32_bf16 v[80:83], v[154:157], v[178:181], 0
	s_and_b64 s[26:27], s[6:7], exec
	s_cselect_b32 s9, s25, s29
	s_cselect_b32 s23, s24, s28
	v_mfma_f32_16x16x32_bf16 v[68:71], v[146:149], v[186:189], 0
	s_ashr_i32 s21, s20, 31
	s_lshl_b64 s[26:27], s[20:21], 19
	s_add_u32 s26, s2, s26
	v_mfma_f32_16x16x32_bf16 v[64:67], v[154:157], v[186:189], 0
	s_addc_u32 s27, s3, s27
	s_and_b64 s[98:99], s[6:7], exec
	s_cselect_b32 s21, s27, s31
	v_mfma_f32_16x16x32_bf16 v[118:121], v[150:153], v[166:169], v[118:121]
	s_cselect_b32 s55, s26, s30
	v_mfma_f32_16x16x32_bf16 v[114:117], v[158:161], v[166:169], v[114:117]
	v_mfma_f32_16x16x32_bf16 v[102:105], v[150:153], v[174:177], v[102:105]
	v_mfma_f32_16x16x32_bf16 v[98:101], v[158:161], v[174:177], v[98:101]
	v_mfma_f32_16x16x32_bf16 v[86:89], v[150:153], v[182:185], v[86:89]
	v_mfma_f32_16x16x32_bf16 v[80:83], v[158:161], v[182:185], v[80:83]
	v_mfma_f32_16x16x32_bf16 v[68:71], v[150:153], v[190:193], v[68:71]
	v_mfma_f32_16x16x32_bf16 v[64:67], v[158:161], v[190:193], v[64:67]
	s_setprio 0
	s_barrier
	s_add_i32 s59, s50, s33
	v_lshl_add_u64 v[194:195], s[30:31], 0, v[212:213]
	s_mov_b32 m0, s59
	ds_read_b128 v[162:165], v241 offset:16384
	ds_read_b128 v[166:169], v246 offset:16384
	ds_read_b128 v[170:173], v241 offset:18432
	ds_read_b128 v[174:177], v246 offset:18432
	ds_read_b128 v[178:181], v241 offset:20480
	ds_read_b128 v[182:185], v246 offset:20480
	ds_read_b128 v[186:189], v241 offset:22528
	ds_read_b128 v[190:193], v246 offset:22528
	global_load_lds_dwordx4 v[194:195], off
	s_add_i32 m0, s59, 0x2000
	s_add_u32 s60, s30, 0x40000
	v_lshl_add_u64 v[196:197], s[30:31], 0, v[216:217]
	s_addc_u32 s61, s31, 0
	s_add_i32 s59, s51, s33
	global_load_lds_dwordx4 v[196:197], off
	v_lshl_add_u64 v[84:85], s[60:61], 0, v[212:213]
	s_mov_b32 m0, s59
	v_lshl_add_u64 v[198:199], s[34:35], 0, v[210:211]
	global_load_lds_dwordx4 v[84:85], off
	v_lshl_add_u64 v[84:85], s[60:61], 0, v[216:217]
	s_add_i32 m0, s59, 0x2000
	v_lshl_add_u64 v[200:201], s[34:35], 0, v[214:215]
	global_load_lds_dwordx4 v[84:85], off
	s_mov_b32 m0, s36
	s_nop 0
	global_load_lds_dwordx4 v[198:199], off
	s_mov_b32 m0, s37
	s_nop 0
	global_load_lds_dwordx4 v[200:201], off
	s_waitcnt vmcnt(8)
	s_waitcnt lgkmcnt(0)
	s_barrier
	s_setprio 0
	s_waitcnt lgkmcnt(0)
	v_mfma_f32_16x16x32_bf16 v[60:63], v[130:133], v[162:165], 0
	v_mfma_f32_16x16x32_bf16 v[56:59], v[138:141], v[162:165], 0
	v_mfma_f32_16x16x32_bf16 v[44:47], v[130:133], v[170:173], 0
	v_mfma_f32_16x16x32_bf16 v[40:43], v[138:141], v[170:173], 0
	v_mfma_f32_16x16x32_bf16 v[28:31], v[130:133], v[178:181], 0
	v_mfma_f32_16x16x32_bf16 v[24:27], v[138:141], v[178:181], 0
	v_mfma_f32_16x16x32_bf16 v[12:15], v[130:133], v[186:189], 0
	v_mfma_f32_16x16x32_bf16 v[8:11], v[138:141], v[186:189], 0
	v_mfma_f32_16x16x32_bf16 v[60:63], v[134:137], v[166:169], v[60:63]
	v_mfma_f32_16x16x32_bf16 v[56:59], v[142:145], v[166:169], v[56:59]
	v_mfma_f32_16x16x32_bf16 v[44:47], v[134:137], v[174:177], v[44:47]
	v_mfma_f32_16x16x32_bf16 v[40:43], v[142:145], v[174:177], v[40:43]
	v_mfma_f32_16x16x32_bf16 v[28:31], v[134:137], v[182:185], v[28:31]
	v_mfma_f32_16x16x32_bf16 v[24:27], v[142:145], v[182:185], v[24:27]
	v_mfma_f32_16x16x32_bf16 v[12:15], v[134:137], v[190:193], v[12:15]
	v_mfma_f32_16x16x32_bf16 v[8:11], v[142:145], v[190:193], v[8:11]
	s_setprio 0
	s_setprio 0
	v_mfma_f32_16x16x32_bf16 v[52:55], v[146:149], v[162:165], 0
	v_mfma_f32_16x16x32_bf16 v[48:51], v[154:157], v[162:165], 0
	v_mfma_f32_16x16x32_bf16 v[36:39], v[146:149], v[170:173], 0
	v_mfma_f32_16x16x32_bf16 v[32:35], v[154:157], v[170:173], 0
	v_mfma_f32_16x16x32_bf16 v[20:23], v[146:149], v[178:181], 0
	v_mfma_f32_16x16x32_bf16 v[16:19], v[154:157], v[178:181], 0
	v_mfma_f32_16x16x32_bf16 v[4:7], v[146:149], v[186:189], 0
	v_mfma_f32_16x16x32_bf16 v[0:3], v[154:157], v[186:189], 0
	v_mfma_f32_16x16x32_bf16 v[52:55], v[150:153], v[166:169], v[52:55]
	v_mfma_f32_16x16x32_bf16 v[48:51], v[158:161], v[166:169], v[48:51]
	v_mfma_f32_16x16x32_bf16 v[36:39], v[150:153], v[174:177], v[36:39]
	v_mfma_f32_16x16x32_bf16 v[32:35], v[158:161], v[174:177], v[32:35]
	v_mfma_f32_16x16x32_bf16 v[20:23], v[150:153], v[182:185], v[20:23]
	v_mfma_f32_16x16x32_bf16 v[16:19], v[158:161], v[182:185], v[16:19]
	v_mfma_f32_16x16x32_bf16 v[4:7], v[150:153], v[190:193], v[4:7]
	v_mfma_f32_16x16x32_bf16 v[0:3], v[158:161], v[190:193], v[0:3]
	s_setprio 0
	s_barrier
	s_add_i32 s59, 0, 0x18000
	v_add_u32_e32 v84, s59, v237
	v_add_u32_e32 v250, s59, v247
	s_add_i32 s60, 0, 0x1c000
	ds_read_b128 v[130:133], v84
	ds_read_b128 v[134:137], v250
	ds_read_b128 v[138:141], v84 offset:2048
	ds_read_b128 v[142:145], v250 offset:2048
	v_add_u32_e32 v84, s60, v237
	v_add_u32_e32 v251, s60, v247
	ds_read_b128 v[146:149], v84
	ds_read_b128 v[150:153], v251
	ds_read_b128 v[154:157], v84 offset:2048
	ds_read_b128 v[158:161], v251 offset:2048
	s_add_u32 s34, s34, 0x40000
	s_addc_u32 s35, s35, 0
	s_mov_b32 m0, s38
	v_lshl_add_u64 v[84:85], s[34:35], 0, v[210:211]
	ds_read_b128 v[162:165], v241 offset:32768
	ds_read_b128 v[166:169], v246 offset:32768
	ds_read_b128 v[170:173], v241 offset:34816
	ds_read_b128 v[174:177], v246 offset:34816
	ds_read_b128 v[178:181], v241 offset:36864
	ds_read_b128 v[182:185], v246 offset:36864
	ds_read_b128 v[186:189], v241 offset:38912
	ds_read_b128 v[190:193], v246 offset:38912
	global_load_lds_dwordx4 v[84:85], off
	v_lshl_add_u64 v[84:85], s[34:35], 0, v[214:215]
	s_mov_b32 m0, s39
	s_nop 0
	global_load_lds_dwordx4 v[84:85], off
	s_waitcnt vmcnt(8)
	s_waitcnt lgkmcnt(0)
	s_barrier
	s_setprio 0
	s_waitcnt lgkmcnt(0)
	v_mfma_f32_16x16x32_bf16 v[126:129], v[130:133], v[162:165], v[126:129]
	v_mfma_f32_16x16x32_bf16 v[122:125], v[138:141], v[162:165], v[122:125]
	v_mfma_f32_16x16x32_bf16 v[110:113], v[130:133], v[170:173], v[110:113]
	v_mfma_f32_16x16x32_bf16 v[106:109], v[138:141], v[170:173], v[106:109]
	v_mfma_f32_16x16x32_bf16 v[94:97], v[130:133], v[178:181], v[94:97]
	v_mfma_f32_16x16x32_bf16 v[90:93], v[138:141], v[178:181], v[90:93]
	v_mfma_f32_16x16x32_bf16 v[76:79], v[130:133], v[186:189], v[76:79]
	v_mfma_f32_16x16x32_bf16 v[72:75], v[138:141], v[186:189], v[72:75]
	v_mfma_f32_16x16x32_bf16 v[126:129], v[134:137], v[166:169], v[126:129]
	v_mfma_f32_16x16x32_bf16 v[122:125], v[142:145], v[166:169], v[122:125]
	v_mfma_f32_16x16x32_bf16 v[110:113], v[134:137], v[174:177], v[110:113]
	v_mfma_f32_16x16x32_bf16 v[106:109], v[142:145], v[174:177], v[106:109]
	v_mfma_f32_16x16x32_bf16 v[94:97], v[134:137], v[182:185], v[94:97]
	v_mfma_f32_16x16x32_bf16 v[90:93], v[142:145], v[182:185], v[90:93]
	v_mfma_f32_16x16x32_bf16 v[76:79], v[134:137], v[190:193], v[76:79]
	v_mfma_f32_16x16x32_bf16 v[72:75], v[142:145], v[190:193], v[72:75]
	s_setprio 0
	s_setprio 0
	v_mfma_f32_16x16x32_bf16 v[118:121], v[146:149], v[162:165], v[118:121]
	v_mfma_f32_16x16x32_bf16 v[114:117], v[154:157], v[162:165], v[114:117]
	v_mfma_f32_16x16x32_bf16 v[102:105], v[146:149], v[170:173], v[102:105]
	v_mfma_f32_16x16x32_bf16 v[98:101], v[154:157], v[170:173], v[98:101]
	v_mfma_f32_16x16x32_bf16 v[84:87], v[146:149], v[178:181], v[86:89]
	v_mfma_f32_16x16x32_bf16 v[80:83], v[154:157], v[178:181], v[80:83]
	v_mfma_f32_16x16x32_bf16 v[68:71], v[146:149], v[186:189], v[68:71]
	v_mfma_f32_16x16x32_bf16 v[64:67], v[154:157], v[186:189], v[64:67]
	v_mfma_f32_16x16x32_bf16 v[118:121], v[150:153], v[166:169], v[118:121]
	v_mfma_f32_16x16x32_bf16 v[114:117], v[158:161], v[166:169], v[114:117]
	v_mfma_f32_16x16x32_bf16 v[102:105], v[150:153], v[174:177], v[102:105]
	v_mfma_f32_16x16x32_bf16 v[98:101], v[158:161], v[174:177], v[98:101]
	v_mfma_f32_16x16x32_bf16 v[86:89], v[150:153], v[182:185], v[84:87]
	v_mfma_f32_16x16x32_bf16 v[82:85], v[158:161], v[182:185], v[80:83]
	v_mfma_f32_16x16x32_bf16 v[68:71], v[150:153], v[190:193], v[68:71]
	v_mfma_f32_16x16x32_bf16 v[64:67], v[158:161], v[190:193], v[64:67]
	s_setprio 0
	s_barrier
	s_add_i32 s34, s59, s33
	v_lshl_add_u64 v[80:81], v[194:195], 0, s[16:17]
	s_mov_b32 m0, s34
	ds_read_b128 v[162:165], v241 offset:49152
	ds_read_b128 v[166:169], v246 offset:49152
	ds_read_b128 v[170:173], v241 offset:51200
	ds_read_b128 v[174:177], v246 offset:51200
	ds_read_b128 v[178:181], v241 offset:53248
	ds_read_b128 v[182:185], v246 offset:53248
	ds_read_b128 v[186:189], v241 offset:55296
	ds_read_b128 v[190:193], v246 offset:55296
	global_load_lds_dwordx4 v[80:81], off
	s_add_i32 m0, s34, 0x2000
	s_add_u32 s30, s30, 0x40080
	v_lshl_add_u64 v[80:81], v[196:197], 0, s[16:17]
	s_addc_u32 s31, s31, 0
	s_add_i32 s34, s60, s33
	global_load_lds_dwordx4 v[80:81], off
	v_lshl_add_u64 v[80:81], s[30:31], 0, v[212:213]
	s_mov_b32 m0, s34
	s_nop 0
	global_load_lds_dwordx4 v[80:81], off
	v_lshl_add_u64 v[80:81], s[30:31], 0, v[216:217]
	s_add_i32 m0, s34, 0x2000
	s_nop 0
	global_load_lds_dwordx4 v[80:81], off
	v_lshl_add_u64 v[80:81], v[198:199], 0, s[16:17]
	s_mov_b32 m0, s47
	s_nop 0
	global_load_lds_dwordx4 v[80:81], off
	v_lshl_add_u64 v[80:81], v[200:201], 0, s[16:17]
	s_mov_b32 m0, s48
	s_nop 0
	global_load_lds_dwordx4 v[80:81], off
	s_waitcnt vmcnt(8)
	s_waitcnt lgkmcnt(0)
	s_barrier
	s_setprio 0
	s_waitcnt lgkmcnt(0)
	v_mfma_f32_16x16x32_bf16 v[60:63], v[130:133], v[162:165], v[60:63]
	v_mfma_f32_16x16x32_bf16 v[56:59], v[138:141], v[162:165], v[56:59]
	v_mfma_f32_16x16x32_bf16 v[44:47], v[130:133], v[170:173], v[44:47]
	v_mfma_f32_16x16x32_bf16 v[40:43], v[138:141], v[170:173], v[40:43]
	v_mfma_f32_16x16x32_bf16 v[28:31], v[130:133], v[178:181], v[28:31]
	v_mfma_f32_16x16x32_bf16 v[24:27], v[138:141], v[178:181], v[24:27]
	v_mfma_f32_16x16x32_bf16 v[12:15], v[130:133], v[186:189], v[12:15]
	v_mfma_f32_16x16x32_bf16 v[8:11], v[138:141], v[186:189], v[8:11]
	v_mfma_f32_16x16x32_bf16 v[60:63], v[134:137], v[166:169], v[60:63]
	v_mfma_f32_16x16x32_bf16 v[56:59], v[142:145], v[166:169], v[56:59]
	v_mfma_f32_16x16x32_bf16 v[44:47], v[134:137], v[174:177], v[44:47]
	v_mfma_f32_16x16x32_bf16 v[40:43], v[142:145], v[174:177], v[40:43]
	v_mfma_f32_16x16x32_bf16 v[28:31], v[134:137], v[182:185], v[28:31]
	v_mfma_f32_16x16x32_bf16 v[24:27], v[142:145], v[182:185], v[24:27]
	v_mfma_f32_16x16x32_bf16 v[12:15], v[134:137], v[190:193], v[12:15]
	v_mfma_f32_16x16x32_bf16 v[8:11], v[142:145], v[190:193], v[8:11]
	s_setprio 0
	s_setprio 0
	v_mfma_f32_16x16x32_bf16 v[52:55], v[146:149], v[162:165], v[52:55]
	v_mfma_f32_16x16x32_bf16 v[48:51], v[154:157], v[162:165], v[48:51]
	v_mfma_f32_16x16x32_bf16 v[36:39], v[146:149], v[170:173], v[36:39]
	v_mfma_f32_16x16x32_bf16 v[32:35], v[154:157], v[170:173], v[32:35]
	v_mfma_f32_16x16x32_bf16 v[20:23], v[146:149], v[178:181], v[20:23]
	v_mfma_f32_16x16x32_bf16 v[16:19], v[154:157], v[178:181], v[16:19]
	v_mfma_f32_16x16x32_bf16 v[4:7], v[146:149], v[186:189], v[4:7]
	v_mfma_f32_16x16x32_bf16 v[0:3], v[154:157], v[186:189], v[0:3]
	v_mfma_f32_16x16x32_bf16 v[52:55], v[150:153], v[166:169], v[52:55]
	v_mfma_f32_16x16x32_bf16 v[48:51], v[158:161], v[166:169], v[48:51]
	v_mfma_f32_16x16x32_bf16 v[36:39], v[150:153], v[174:177], v[36:39]
	v_mfma_f32_16x16x32_bf16 v[32:35], v[158:161], v[174:177], v[32:35]
	v_mfma_f32_16x16x32_bf16 v[20:23], v[150:153], v[182:185], v[20:23]
	v_mfma_f32_16x16x32_bf16 v[16:19], v[158:161], v[182:185], v[16:19]
	v_mfma_f32_16x16x32_bf16 v[4:7], v[150:153], v[190:193], v[4:7]
	v_mfma_f32_16x16x32_bf16 v[0:3], v[158:161], v[190:193], v[0:3]
	s_setprio 0
	s_barrier
	s_add_i32 s58, s58, 2
	s_add_u32 s28, s28, 0x100
	s_addc_u32 s29, s29, 0
	s_add_u32 s56, s56, 0x100
	s_addc_u32 s57, s57, 0
	s_cmp_gt_u32 s58, 13

.LBB0_1110:
	s_add_u32 s24, s24, 0x40080
	s_addc_u32 s25, s25, 0
	s_add_u32 s53, s26, 0x100
	s_addc_u32 s54, s27, 0
	s_mov_b32 s55, -2
	s_waitcnt vmcnt(0)
	v_xor_b32_e32 v246, 64, v179
	v_xor_b32_e32 v247, 64, v167
	v_add_u32_e32 v248, s46, v247
	v_add_u32_e32 v249, s47, v247
	ds_read_b128 v[124:127], v171
	ds_read_b128 v[132:135], v248
	ds_read_b128 v[136:139], v171 offset:2048
	ds_read_b128 v[140:143], v248 offset:2048
	ds_read_b128 v[162:165], v175
	ds_read_b128 v[182:185], v249
	ds_read_b128 v[186:189], v175 offset:2048
	ds_read_b128 v[190:193], v249 offset:2048
	s_add_u32 s26, s24, 0xfffc0080
	s_addc_u32 s27, s25, -1
	s_cmp_eq_u32 s55, 12
	s_cselect_b32 s29, s17, s27
	s_cselect_b32 s28, s51, s26
	s_cselect_b32 s27, s15, s54
	s_cselect_b32 s26, s52, s53
	v_lshl_add_u64 v[172:173], s[24:25], 0, v[152:153]
	s_add_i32 m0, s23, 0xc000
	ds_read_b128 v[194:197], v179
	ds_read_b128 v[198:201], v246
	ds_read_b128 v[202:205], v179 offset:2048
	ds_read_b128 v[206:209], v246 offset:2048
	ds_read_b128 v[210:213], v179 offset:4096
	ds_read_b128 v[214:217], v246 offset:4096
	ds_read_b128 v[218:221], v179 offset:6144
	ds_read_b128 v[222:225], v246 offset:6144
	global_load_lds_dwordx4 v[172:173], off
	v_lshl_add_u64 v[172:173], s[24:25], 0, v[154:155]
	s_add_i32 m0, s23, 0xe000
	s_nop 0
	global_load_lds_dwordx4 v[172:173], off
	s_waitcnt vmcnt(8)
	s_waitcnt lgkmcnt(0)
	s_barrier
	s_setprio 0
	s_waitcnt lgkmcnt(0)
	v_mfma_f32_16x16x32_bf16 v[128:131], v[124:127], v[194:197], 0
	s_add_i32 s39, s39, 1
	s_mul_i32 s0, s39, s42
	s_mul_hi_u32 s1, s39, s45
	v_mfma_f32_16x16x32_bf16 v[120:123], v[136:139], v[194:197], 0
	s_add_i32 s1, s1, s0
	s_mul_i32 s0, s39, s45
	s_add_u32 s18, s0, s96
	v_mfma_f32_16x16x32_bf16 v[108:111], v[124:127], v[202:205], 0
	s_addc_u32 s19, s1, s34
	v_cmp_lt_i64_e64 s[0:1], s[18:19], v[156:157]
	s_ashr_i32 s14, s18, 31
	v_mfma_f32_16x16x32_bf16 v[104:107], v[136:139], v[202:205], 0
	s_lshr_b32 s14, s14, 29
	s_add_i32 s14, s18, s14
	s_ashr_i32 s15, s14, 3
	v_mfma_f32_16x16x32_bf16 v[92:95], v[124:127], v[210:213], 0
	s_and_b32 s14, s14, -8
	s_sub_i32 s14, s18, s14
	s_cmp_lt_i32 s14, 0
	v_mfma_f32_16x16x32_bf16 v[88:91], v[136:139], v[210:213], 0
	s_cselect_b32 s16, s35, 0x160
	s_mul_i32 s14, s14, s16
	s_add_i32 s14, s14, s15
	v_mfma_f32_16x16x32_bf16 v[76:79], v[124:127], v[218:221], 0
	s_mul_hi_i32 s15, s14, 0x2e8ba2e9
	s_lshr_b32 s16, s15, 31
	s_ashr_i32 s15, s15, 5
	v_mfma_f32_16x16x32_bf16 v[72:75], v[136:139], v[218:221], 0
	s_add_i32 s15, s15, s16
	s_lshl_b32 s16, s15, 3
	s_sub_i32 s17, 0x80, s16
	v_mfma_f32_16x16x32_bf16 v[128:131], v[132:135], v[198:201], v[128:131]
	s_min_i32 s17, s17, 8
	s_abs_i32 s18, s17
	v_cvt_f32_u32_e32 v252, s18
	v_mfma_f32_16x16x32_bf16 v[120:123], v[140:143], v[198:201], v[120:123]
	s_sub_i32 s20, 0, s18
	s_mulk_i32 s15, 0xb0
	s_sub_i32 s15, s14, s15
	v_mfma_f32_16x16x32_bf16 v[108:111], v[132:135], v[206:209], v[108:111]
	v_rcp_iflag_f32_e32 v252, v252
	s_abs_i32 s14, s15
	s_xor_b32 s19, s15, s17
	v_mfma_f32_16x16x32_bf16 v[104:107], v[140:143], v[206:209], v[104:107]
	s_ashr_i32 s19, s19, 31
	v_mul_f32_e32 v252, 0x4f7ffffe, v252
	v_cvt_u32_f32_e32 v252, v252
	v_mfma_f32_16x16x32_bf16 v[92:95], v[132:135], v[214:217], v[92:95]
	s_nop 0
	v_readfirstlane_b32 s21, v252
	s_mul_i32 s20, s20, s21
	v_mfma_f32_16x16x32_bf16 v[88:91], v[140:143], v[214:217], v[88:91]
	s_mul_hi_u32 s20, s21, s20
	s_add_i32 s21, s21, s20
	s_mul_hi_u32 s20, s14, s21
	v_mfma_f32_16x16x32_bf16 v[76:79], v[132:135], v[222:225], v[76:79]
	s_mul_i32 s21, s20, s18
	s_sub_i32 s14, s14, s21
	s_add_i32 s98, s20, 1
	v_mfma_f32_16x16x32_bf16 v[72:75], v[140:143], v[222:225], v[72:75]
	s_sub_i32 s21, s14, s18
	s_cmp_ge_u32 s14, s18
	s_cselect_b32 s20, s98, s20
	s_setprio 0
	s_setprio 0
	v_mfma_f32_16x16x32_bf16 v[116:119], v[162:165], v[194:197], 0
	s_cselect_b32 s14, s21, s14
	s_add_i32 s21, s20, 1
	s_cmp_ge_u32 s14, s18
	v_mfma_f32_16x16x32_bf16 v[112:115], v[186:189], v[194:197], 0
	s_cselect_b32 s14, s21, s20
	s_xor_b32 s14, s14, s19
	s_sub_i32 s14, s14, s19
	v_mfma_f32_16x16x32_bf16 v[100:103], v[162:165], v[202:205], 0
	s_mul_i32 s17, s14, s17
	s_sub_i32 s15, s15, s17
	s_add_i32 s16, s16, s15
	v_mfma_f32_16x16x32_bf16 v[96:99], v[186:189], v[202:205], 0
	s_ashr_i32 s17, s16, 31
	s_lshl_b64 s[18:19], s[16:17], 19
	s_add_u32 s18, s2, s18
	v_mfma_f32_16x16x32_bf16 v[84:87], v[162:165], v[210:213], 0
	s_addc_u32 s19, s3, s19
	s_and_b64 s[20:21], s[0:1], exec
	s_cselect_b32 s17, s19, s25
	v_mfma_f32_16x16x32_bf16 v[80:83], v[186:189], v[210:213], 0
	s_cselect_b32 s51, s18, s24
	s_ashr_i32 s15, s14, 31
	s_lshl_b64 s[20:21], s[14:15], 19
	v_mfma_f32_16x16x32_bf16 v[68:71], v[162:165], v[218:221], 0
	s_add_u32 s20, s30, s20
	s_addc_u32 s21, s31, s21
	s_and_b64 s[98:99], s[0:1], exec
	v_mfma_f32_16x16x32_bf16 v[64:67], v[186:189], v[218:221], 0
	s_cselect_b32 s15, s21, s27
	s_cselect_b32 s52, s20, s26
	v_mfma_f32_16x16x32_bf16 v[116:119], v[182:185], v[198:201], v[116:119]
	v_mfma_f32_16x16x32_bf16 v[112:115], v[190:193], v[198:201], v[112:115]
	v_mfma_f32_16x16x32_bf16 v[100:103], v[182:185], v[206:209], v[100:103]
	v_mfma_f32_16x16x32_bf16 v[96:99], v[190:193], v[206:209], v[96:99]
	v_mfma_f32_16x16x32_bf16 v[84:87], v[182:185], v[214:217], v[84:87]
	v_mfma_f32_16x16x32_bf16 v[80:83], v[190:193], v[214:217], v[80:83]
	v_mfma_f32_16x16x32_bf16 v[68:71], v[182:185], v[222:225], v[68:71]
	v_mfma_f32_16x16x32_bf16 v[64:67], v[190:193], v[222:225], v[64:67]
	s_setprio 0
	s_barrier
	s_add_i32 s56, s46, s33
	v_lshl_add_u64 v[172:173], s[26:27], 0, v[148:149]
	s_mov_b32 m0, s56
	ds_read_b128 v[194:197], v179 offset:16384
	ds_read_b128 v[198:201], v246 offset:16384
	ds_read_b128 v[202:205], v179 offset:18432
	ds_read_b128 v[206:209], v246 offset:18432
	ds_read_b128 v[210:213], v179 offset:20480
	ds_read_b128 v[214:217], v246 offset:20480
	ds_read_b128 v[218:221], v179 offset:22528
	ds_read_b128 v[222:225], v246 offset:22528
	global_load_lds_dwordx4 v[172:173], off
	s_add_i32 m0, s56, 0x2000
	s_add_u32 s56, s26, 0x40000
	v_lshl_add_u64 v[176:177], s[26:27], 0, v[144:145]
	s_addc_u32 s57, s27, 0
	s_add_i32 s58, s47, s33
	global_load_lds_dwordx4 v[176:177], off
	v_lshl_add_u64 v[226:227], s[56:57], 0, v[148:149]
	s_mov_b32 m0, s58
	v_lshl_add_u64 v[228:229], s[28:29], 0, v[146:147]
	global_load_lds_dwordx4 v[226:227], off
	v_lshl_add_u64 v[226:227], s[56:57], 0, v[144:145]
	s_add_i32 m0, s58, 0x2000
	s_nop 0
	global_load_lds_dwordx4 v[226:227], off
	v_lshl_add_u64 v[226:227], s[28:29], 0, v[150:151]
	s_mov_b32 m0, s23
	s_nop 0
	global_load_lds_dwordx4 v[226:227], off
	s_mov_b32 m0, s36
	s_nop 0
	global_load_lds_dwordx4 v[228:229], off
	s_waitcnt vmcnt(8)
	s_waitcnt lgkmcnt(0)
	s_barrier
	s_setprio 0
	s_waitcnt lgkmcnt(0)
	v_mfma_f32_16x16x32_bf16 v[60:63], v[124:127], v[194:197], 0
	v_mfma_f32_16x16x32_bf16 v[56:59], v[136:139], v[194:197], 0
	v_mfma_f32_16x16x32_bf16 v[44:47], v[124:127], v[202:205], 0
	v_mfma_f32_16x16x32_bf16 v[40:43], v[136:139], v[202:205], 0
	v_mfma_f32_16x16x32_bf16 v[28:31], v[124:127], v[210:213], 0
	v_mfma_f32_16x16x32_bf16 v[24:27], v[136:139], v[210:213], 0
	v_mfma_f32_16x16x32_bf16 v[12:15], v[124:127], v[218:221], 0
	v_mfma_f32_16x16x32_bf16 v[8:11], v[136:139], v[218:221], 0
	v_mfma_f32_16x16x32_bf16 v[60:63], v[132:135], v[198:201], v[60:63]
	v_mfma_f32_16x16x32_bf16 v[56:59], v[140:143], v[198:201], v[56:59]
	v_mfma_f32_16x16x32_bf16 v[44:47], v[132:135], v[206:209], v[44:47]
	v_mfma_f32_16x16x32_bf16 v[40:43], v[140:143], v[206:209], v[40:43]
	v_mfma_f32_16x16x32_bf16 v[28:31], v[132:135], v[214:217], v[28:31]
	v_mfma_f32_16x16x32_bf16 v[24:27], v[140:143], v[214:217], v[24:27]
	v_mfma_f32_16x16x32_bf16 v[12:15], v[132:135], v[222:225], v[12:15]
	v_mfma_f32_16x16x32_bf16 v[8:11], v[140:143], v[222:225], v[8:11]
	s_setprio 0
	s_setprio 0
	v_mfma_f32_16x16x32_bf16 v[52:55], v[162:165], v[194:197], 0
	v_mfma_f32_16x16x32_bf16 v[48:51], v[186:189], v[194:197], 0
	v_mfma_f32_16x16x32_bf16 v[36:39], v[162:165], v[202:205], 0
	v_mfma_f32_16x16x32_bf16 v[32:35], v[186:189], v[202:205], 0
	v_mfma_f32_16x16x32_bf16 v[20:23], v[162:165], v[210:213], 0
	v_mfma_f32_16x16x32_bf16 v[16:19], v[186:189], v[210:213], 0
	v_mfma_f32_16x16x32_bf16 v[4:7], v[162:165], v[218:221], 0
	v_mfma_f32_16x16x32_bf16 v[0:3], v[186:189], v[218:221], 0
	v_mfma_f32_16x16x32_bf16 v[52:55], v[182:185], v[198:201], v[52:55]
	v_mfma_f32_16x16x32_bf16 v[48:51], v[190:193], v[198:201], v[48:51]
	v_mfma_f32_16x16x32_bf16 v[36:39], v[182:185], v[206:209], v[36:39]
	v_mfma_f32_16x16x32_bf16 v[32:35], v[190:193], v[206:209], v[32:35]
	v_mfma_f32_16x16x32_bf16 v[20:23], v[182:185], v[214:217], v[20:23]
	v_mfma_f32_16x16x32_bf16 v[16:19], v[190:193], v[214:217], v[16:19]
	v_mfma_f32_16x16x32_bf16 v[4:7], v[182:185], v[222:225], v[4:7]
	v_mfma_f32_16x16x32_bf16 v[0:3], v[190:193], v[222:225], v[0:3]
	s_setprio 0
	s_barrier
	s_add_i32 s56, 0, 0x18000
	s_add_i32 s57, 0, 0x1c000
	v_add_u32_e32 v140, s56, v167
	v_add_u32_e32 v250, s56, v247
	v_add_u32_e32 v160, s57, v167
	v_add_u32_e32 v251, s57, v247
	ds_read_b128 v[124:127], v140
	ds_read_b128 v[132:135], v250
	ds_read_b128 v[136:139], v140 offset:2048
	ds_read_b128 v[140:143], v250 offset:2048
	ds_read_b128 v[162:165], v160
	ds_read_b128 v[182:185], v251
	ds_read_b128 v[186:189], v160 offset:2048
	ds_read_b128 v[190:193], v251 offset:2048
	s_add_u32 s28, s28, 0x40000
	s_addc_u32 s29, s29, 0
	s_mov_b32 m0, s37
	v_lshl_add_u64 v[230:231], s[28:29], 0, v[150:151]
	ds_read_b128 v[194:197], v179 offset:32768
	ds_read_b128 v[198:201], v246 offset:32768
	ds_read_b128 v[202:205], v179 offset:34816
	ds_read_b128 v[206:209], v246 offset:34816
	ds_read_b128 v[210:213], v179 offset:36864
	ds_read_b128 v[214:217], v246 offset:36864
	ds_read_b128 v[218:221], v179 offset:38912
	ds_read_b128 v[222:225], v246 offset:38912
	global_load_lds_dwordx4 v[230:231], off
	v_lshl_add_u64 v[230:231], s[28:29], 0, v[146:147]
	s_mov_b32 m0, s38
	s_nop 0
	global_load_lds_dwordx4 v[230:231], off
	s_waitcnt vmcnt(8)
	s_waitcnt lgkmcnt(0)
	s_barrier
	s_setprio 0
	s_waitcnt lgkmcnt(0)
	v_mfma_f32_16x16x32_bf16 v[128:131], v[124:127], v[194:197], v[128:131]
	v_mfma_f32_16x16x32_bf16 v[120:123], v[136:139], v[194:197], v[120:123]
	v_mfma_f32_16x16x32_bf16 v[108:111], v[124:127], v[202:205], v[108:111]
	v_mfma_f32_16x16x32_bf16 v[104:107], v[136:139], v[202:205], v[104:107]
	v_mfma_f32_16x16x32_bf16 v[92:95], v[124:127], v[210:213], v[92:95]
	v_mfma_f32_16x16x32_bf16 v[88:91], v[136:139], v[210:213], v[88:91]
	v_mfma_f32_16x16x32_bf16 v[76:79], v[124:127], v[218:221], v[76:79]
	v_mfma_f32_16x16x32_bf16 v[72:75], v[136:139], v[218:221], v[72:75]
	v_mfma_f32_16x16x32_bf16 v[128:131], v[132:135], v[198:201], v[128:131]
	v_mfma_f32_16x16x32_bf16 v[120:123], v[140:143], v[198:201], v[120:123]
	v_mfma_f32_16x16x32_bf16 v[108:111], v[132:135], v[206:209], v[108:111]
	v_mfma_f32_16x16x32_bf16 v[104:107], v[140:143], v[206:209], v[104:107]
	v_mfma_f32_16x16x32_bf16 v[92:95], v[132:135], v[214:217], v[92:95]
	v_mfma_f32_16x16x32_bf16 v[88:91], v[140:143], v[214:217], v[88:91]
	v_mfma_f32_16x16x32_bf16 v[76:79], v[132:135], v[222:225], v[76:79]
	v_mfma_f32_16x16x32_bf16 v[72:75], v[140:143], v[222:225], v[72:75]
	s_setprio 0
	s_setprio 0
	v_mfma_f32_16x16x32_bf16 v[116:119], v[162:165], v[194:197], v[116:119]
	v_mfma_f32_16x16x32_bf16 v[112:115], v[186:189], v[194:197], v[112:115]
	v_mfma_f32_16x16x32_bf16 v[100:103], v[162:165], v[202:205], v[100:103]
	v_mfma_f32_16x16x32_bf16 v[96:99], v[186:189], v[202:205], v[96:99]
	v_mfma_f32_16x16x32_bf16 v[84:87], v[162:165], v[210:213], v[84:87]
	v_mfma_f32_16x16x32_bf16 v[80:83], v[186:189], v[210:213], v[80:83]
	v_mfma_f32_16x16x32_bf16 v[68:71], v[162:165], v[218:221], v[68:71]
	v_mfma_f32_16x16x32_bf16 v[64:67], v[186:189], v[218:221], v[64:67]
	v_mfma_f32_16x16x32_bf16 v[116:119], v[182:185], v[198:201], v[116:119]
	v_mfma_f32_16x16x32_bf16 v[112:115], v[190:193], v[198:201], v[112:115]
	v_mfma_f32_16x16x32_bf16 v[100:103], v[182:185], v[206:209], v[100:103]
	v_mfma_f32_16x16x32_bf16 v[96:99], v[190:193], v[206:209], v[96:99]
	v_mfma_f32_16x16x32_bf16 v[84:87], v[182:185], v[214:217], v[84:87]
	v_mfma_f32_16x16x32_bf16 v[80:83], v[190:193], v[214:217], v[80:83]
	v_mfma_f32_16x16x32_bf16 v[68:71], v[182:185], v[222:225], v[68:71]
	v_mfma_f32_16x16x32_bf16 v[64:67], v[190:193], v[222:225], v[64:67]
	s_setprio 0
	s_barrier
	s_add_i32 s28, s56, s33
	v_lshl_add_u64 v[172:173], v[172:173], 0, s[10:11]
	s_mov_b32 m0, s28
	ds_read_b128 v[194:197], v179 offset:49152
	ds_read_b128 v[198:201], v246 offset:49152
	ds_read_b128 v[202:205], v179 offset:51200
	ds_read_b128 v[206:209], v246 offset:51200
	ds_read_b128 v[210:213], v179 offset:53248
	ds_read_b128 v[214:217], v246 offset:53248
	ds_read_b128 v[218:221], v179 offset:55296
	ds_read_b128 v[222:225], v246 offset:55296
	global_load_lds_dwordx4 v[172:173], off
	s_add_i32 m0, s28, 0x2000
	s_add_u32 s26, s26, 0x40080
	v_lshl_add_u64 v[172:173], v[176:177], 0, s[10:11]
	s_addc_u32 s27, s27, 0
	s_add_i32 s28, s57, s33
	global_load_lds_dwordx4 v[172:173], off
	v_lshl_add_u64 v[172:173], s[26:27], 0, v[148:149]
	s_mov_b32 m0, s28
	s_nop 0
	global_load_lds_dwordx4 v[172:173], off
	v_lshl_add_u64 v[172:173], s[26:27], 0, v[144:145]
	s_add_i32 m0, s28, 0x2000
	s_nop 0
	global_load_lds_dwordx4 v[172:173], off
	v_lshl_add_u64 v[172:173], v[226:227], 0, s[10:11]
	s_mov_b32 m0, s43
	s_nop 0
	global_load_lds_dwordx4 v[172:173], off
	v_lshl_add_u64 v[172:173], v[228:229], 0, s[10:11]
	s_mov_b32 m0, s44
	s_nop 0
	global_load_lds_dwordx4 v[172:173], off
	s_waitcnt vmcnt(8)
	s_waitcnt lgkmcnt(0)
	s_barrier
	s_setprio 0
	s_waitcnt lgkmcnt(0)
	v_mfma_f32_16x16x32_bf16 v[60:63], v[124:127], v[194:197], v[60:63]
	v_mfma_f32_16x16x32_bf16 v[56:59], v[136:139], v[194:197], v[56:59]
	v_mfma_f32_16x16x32_bf16 v[44:47], v[124:127], v[202:205], v[44:47]
	v_mfma_f32_16x16x32_bf16 v[40:43], v[136:139], v[202:205], v[40:43]
	v_mfma_f32_16x16x32_bf16 v[28:31], v[124:127], v[210:213], v[28:31]
	v_mfma_f32_16x16x32_bf16 v[24:27], v[136:139], v[210:213], v[24:27]
	v_mfma_f32_16x16x32_bf16 v[12:15], v[124:127], v[218:221], v[12:15]
	v_mfma_f32_16x16x32_bf16 v[8:11], v[136:139], v[218:221], v[8:11]
	v_mfma_f32_16x16x32_bf16 v[60:63], v[132:135], v[198:201], v[60:63]
	v_mfma_f32_16x16x32_bf16 v[56:59], v[140:143], v[198:201], v[56:59]
	v_mfma_f32_16x16x32_bf16 v[44:47], v[132:135], v[206:209], v[44:47]
	v_mfma_f32_16x16x32_bf16 v[40:43], v[140:143], v[206:209], v[40:43]
	v_mfma_f32_16x16x32_bf16 v[28:31], v[132:135], v[214:217], v[28:31]
	v_mfma_f32_16x16x32_bf16 v[24:27], v[140:143], v[214:217], v[24:27]
	v_mfma_f32_16x16x32_bf16 v[12:15], v[132:135], v[222:225], v[12:15]
	v_mfma_f32_16x16x32_bf16 v[8:11], v[140:143], v[222:225], v[8:11]
	s_setprio 0
	s_setprio 0
	v_mfma_f32_16x16x32_bf16 v[52:55], v[162:165], v[194:197], v[52:55]
	v_mfma_f32_16x16x32_bf16 v[48:51], v[186:189], v[194:197], v[48:51]
	v_mfma_f32_16x16x32_bf16 v[36:39], v[162:165], v[202:205], v[36:39]
	v_mfma_f32_16x16x32_bf16 v[32:35], v[186:189], v[202:205], v[32:35]
	v_mfma_f32_16x16x32_bf16 v[20:23], v[162:165], v[210:213], v[20:23]
	v_mfma_f32_16x16x32_bf16 v[16:19], v[186:189], v[210:213], v[16:19]
	v_mfma_f32_16x16x32_bf16 v[4:7], v[162:165], v[218:221], v[4:7]
	v_mfma_f32_16x16x32_bf16 v[0:3], v[186:189], v[218:221], v[0:3]
	v_mfma_f32_16x16x32_bf16 v[52:55], v[182:185], v[198:201], v[52:55]
	v_mfma_f32_16x16x32_bf16 v[48:51], v[190:193], v[198:201], v[48:51]
	v_mfma_f32_16x16x32_bf16 v[36:39], v[182:185], v[206:209], v[36:39]
	v_mfma_f32_16x16x32_bf16 v[32:35], v[190:193], v[206:209], v[32:35]
	v_mfma_f32_16x16x32_bf16 v[20:23], v[182:185], v[214:217], v[20:23]
	v_mfma_f32_16x16x32_bf16 v[16:19], v[190:193], v[214:217], v[16:19]
	v_mfma_f32_16x16x32_bf16 v[4:7], v[182:185], v[222:225], v[4:7]
	v_mfma_f32_16x16x32_bf16 v[0:3], v[190:193], v[222:225], v[0:3]
	s_setprio 0
	s_barrier
	s_add_i32 s55, s55, 2
	s_add_u32 s24, s24, 0x100
	s_addc_u32 s25, s25, 0
	s_add_u32 s53, s53, 0x100
	s_addc_u32 s54, s54, 0
	s_cmp_gt_u32 s55, 13
